# DSA tile loop: K/V tile DMA and mask load addressed as SGPR base + 32-bit VGPR offset; the per-tile pointer advance is 6 SALU adds instead of 11 64-bit VALU adds
# speedup vs baseline: 1.0069x; 1.0069x over previous
; #define LAS __attribute__((address_space(3)))
; template <int MODE>
; __device__ __forceinline__ void attn_unit(LAS char* lds, const AttnPtrs& A, int b, int qb) {
;     ...
;     const int tid = opaque_tid(), lane = tid & 63, r32 = lane & 31, hi = lane >> 5, wid = __builtin_amdgcn_readfirstlane(tid >> 6);
;     const int strm = (MODE == 2) ? (wid & 1) : 0;
;     const size_t rowbase = (size_t)b * SEQ; const int q0 = (MODE == 2) ? qb * 128 + (wid >> 1) * 32 : qb * 256 + wid * 32; const int cw = q0 >> 6, NT = (MODE == 2) ? 2 * qb + 2 : 4 * qb + 4;
;     const size_t qrow = rowbase + q0 + r32;
;     const bf16_t* ksrc[2]; const bf16_t* vsrc[2];
; #pragma unroll
;     for (int i = 0; i < 2; ++i) { const unsigned row = 4u * (2 * wid + i) + (lane >> 4), ch = (lane & 15) ^ (((row & 3) << 2) | ((row >> 2) & 3));
;         ksrc[i] = A.K + (rowbase + row) * A.ldk + ch * 8; vsrc[i] = A.V + (rowbase + row) * A.ldv + ch * 8; }
;     const bf16_t* k64src = nullptr;
;     if constexpr (MODE == 0) { const unsigned row = 8u * wid + (lane >> 3), ch = (lane & 7) ^ ((row >> 1) & 7); k64src = A.K64 + (rowbase + row) * 64 + ch * 8; }
;     const unsigned fK = ((r32 & 3) << 2) | ((r32 >> 2) & 3);
;     const unsigned g64 = (r32 >> 1) & 7;
;     const int q4 = (lane & 15) >> 2, p4 = lane & 3, blk = (lane >> 4) & 1;
;     unsigned vrow[2], vlow[2];
; #pragma unroll
;     for (int t = 0; t < 2; ++t) { vrow[t] = 4 * hi + 8 * t + q4; vlow[t] = (unsigned)((2 * blk + (p4 >> 1)) ^ ((hi + 2 * t) & 3)); }
;     ...
;     STAGE(0, 0); STAGE(1, 1);
;     bf16x8 qf[NQ];
; #pragma unroll
;     for (int s = 0; s < NQ; ++s) qf[s] = *(const bf16x8*)(A.Q + qrow * A.ldq + 64 * strm + 16 * s + 8 * hi);
;     if constexpr (MODE == 0) {
; #pragma unroll
;         for (int s = 0; s < 4; ++s) {
;             const u32x4 w = __builtin_bit_cast(u32x4, qf[8 + s]);
;             const f32x4 t0 = *(const f32x4*)(A.subg + (qrow * 56 + 8 * s + 4 * hi) * 2), t1 = *(const f32x4*)(A.subg + (qrow * 56 + 8 * s + 4 * hi) * 2 + 4);
;             u32x4 o;
;     ...
;                 } else { const int w2 = w - 24, b = w2 / 5, h = w2 % 5;
;                     att::AttnPtrs A{QKB + h * 128, 1280, QKB + 640 + h * 128, 1280, nullptr, VBC + h * 128, 1280, GATE + 768 + h * 128, GATE + 768 + h * 128, MASK, 0.f, 0.f, nullptr};
;     ...
;                     att::attn_unit<1>((LAS char*)lds, A, b, qb);
.LBB0_1168:
	s_mul_hi_i32 s1, s0, 0xd1745d17
	s_lshr_b32 s12, s1, 31
	s_ashr_i32 s1, s1, 3
	s_add_i32 s49, s1, s12
	s_mul_hi_i32 s1, s0, 0x2e8ba2e9
	s_lshr_b32 s12, s1, 31
	s_ashr_i32 s1, s1, 3
	s_add_i32 s1, s1, s12
	s_mul_i32 s1, s1, 44
	s_add_i32 s49, s49, 15
	s_sub_i32 s14, s0, s1
	s_cmp_gt_i32 s14, 23
	s_mov_b64 s[0:1], -1
	s_cbranch_scc0 .LBB0_1186
	s_add_i32 s0, s14, 0xffe8
	s_and_b32 s12, s0, 0xff
	s_mul_i32 s1, s12, 0xcd
	s_bfe_u32 s13, s1, 0x6000a
	s_mul_i32 s1, s13, 5
	s_sub_i32 s0, s0, s1
	s_and_b32 s0, s0, 0xff
	s_lshl_b32 s15, s0, 7
	s_lshl_b32 s16, s0, 8
	s_add_u32 s0, s21, s16
	s_addc_u32 s1, s22, 0
	s_add_u32 s50, s23, s16
	s_addc_u32 s51, s24, 0
	s_add_u32 s52, s25, s16
	s_getreg_b32 s17, hwreg(HW_REG_HW_ID, 0, 6)
	s_addc_u32 s53, s26, 0
	s_lshl_b32 s17, s17, 2
	s_and_b32 s17, s17, 0xfc
	s_add_i32 s17, s17, 0x20040
	v_mov_b32_e32 v0, s17
	ds_read_b32 v0, v0
	s_lshl_b32 s68, s13, 12
	v_mov_b64_e32 v[6:7], s[50:51]
	v_mov_b32_e32 v3, v1
	s_mul_i32 s13, s13, 0x9ffb00
	s_waitcnt lgkmcnt(0)
	v_readfirstlane_b32 s18, v0
	v_mov_b32_e32 v0, v1
	s_mov_b32 s16, 2
	v_mbcnt_lo_u32_b32 v0, -1, v0
	v_mbcnt_hi_u32_b32 v8, -1, v0
	v_lshl_or_b32 v0, s18, 6, v8
	v_bfe_u32 v9, v8, 4, 2
	v_readfirstlane_b32 s18, v0
	s_ashr_i32 s19, s18, 6
	s_lshl_b32 s18, s49, 8
	s_lshl_b32 s33, s19, 5
	s_add_i32 s54, s33, s18
	s_lshl_b32 s18, s19, 3
	v_or_b32_e32 v0, s18, v9
	s_lshl_b32 s56, s19, 1
	v_and_b32_e32 v13, 15, v8
	v_lshlrev_b32_e32 v20, 2, v9
	s_and_b32 s56, s56, 2
	v_lshl_add_u64 v[4:5], s[68:69], 0, v[0:1]
	v_bitop3_b32 v2, s56, v13, v20 bitop3:0x36
	v_mad_u64_u32 v[10:11], s[50:51], v4, s84, v[6:7]
	v_mad_u32_u24 v11, v5, s84, v11
	v_lshlrev_b32_e32 v2, 4, v2
	v_lshl_add_u64 v[16:17], v[10:11], 0, v[2:3]
	v_mov_b64_e32 v[10:11], s[52:53]
	v_mad_u64_u32 v[14:15], s[50:51], v4, s84, v[10:11]
	s_or_b32 s18, s18, 4
	v_mad_u32_u24 v15, v5, s84, v15
	v_or_b32_e32 v4, s18, v9
	v_mov_b32_e32 v5, v1
	v_lshl_add_u64 v[18:19], v[14:15], 0, v[2:3]
	s_bfe_u32 s18, s18, 0x20002
	v_lshl_add_u64 v[14:15], s[68:69], 0, v[4:5]
	s_lshl_b32 s33, s49, 2
	s_ashr_i32 s55, s54, 31
	v_bitop3_b32 v9, s18, v13, v20 bitop3:0x36
	v_mad_u64_u32 v[6:7], s[50:51], v14, s84, v[6:7]
	v_mad_u64_u32 v[10:11], s[50:51], v14, s84, v[10:11]
	s_ashr_i32 s18, s54, 6
	s_add_u32 s50, s68, s54
	s_addc_u32 s51, 0, s55
	s_lshl_b32 s19, s19, 11
	s_add_i32 s19, s19, 0
	v_mad_u32_u24 v7, v15, s84, v7
	v_lshlrev_b32_e32 v4, 4, v9
	s_mov_b32 m0, s19
	v_lshl_add_u64 v[6:7], v[6:7], 0, v[4:5]
	global_load_lds_dwordx4 v[16:17], off
	s_add_i32 m0, s19, 0x400
	v_mad_u32_u24 v11, v15, s84, v11
	global_load_lds_dwordx4 v[6:7], off
	s_add_i32 m0, s19, 0x4000
	v_lshl_add_u64 v[20:21], v[10:11], 0, v[4:5]
	global_load_lds_dwordx4 v[18:19], off
	s_add_i32 m0, s19, 0x4400
	v_lshl_add_u64 v[16:17], v[16:17], 0, s[60:61]
	global_load_lds_dwordx4 v[20:21], off
	s_add_i32 m0, s19, 0xa000
	v_lshl_add_u64 v[6:7], v[6:7], 0, s[60:61]
	global_load_lds_dwordx4 v[16:17], off
	s_add_i32 m0, s19, 0xa400
	v_and_b32_e32 v12, 31, v8
	global_load_lds_dwordx4 v[6:7], off
	v_lshl_add_u64 v[6:7], v[18:19], 0, s[60:61]
	s_add_i32 m0, s19, 0xe000
	v_or_b32_e32 v130, s50, v12
	global_load_lds_dwordx4 v[6:7], off
	v_lshl_add_u64 v[6:7], v[20:21], 0, s[60:61]
	s_add_i32 m0, s19, 0xe400
	v_bfe_u32 v9, v8, 5, 1
	global_load_lds_dwordx4 v[6:7], off
	v_mov_b64_e32 v[6:7], s[0:1]
	v_mad_u64_u32 v[6:7], s[0:1], v130, s84, v[6:7]
	v_mov_b32_e32 v16, 0xa00
	v_mad_i32_i24 v7, s51, v16, v7
	v_lshlrev_b32_e32 v16, 4, v9
	v_mov_b32_e32 v17, v1
	v_lshl_add_u64 v[6:7], v[6:7], 0, v[16:17]
	global_load_dwordx4 v[98:101], v[6:7], off
	global_load_dwordx4 v[102:105], v[6:7], off offset:32
	global_load_dwordx4 v[106:109], v[6:7], off offset:64
	global_load_dwordx4 v[110:113], v[6:7], off offset:96
	global_load_dwordx4 v[114:117], v[6:7], off offset:128
	global_load_dwordx4 v[118:121], v[6:7], off offset:160
	global_load_dwordx4 v[122:125], v[6:7], off offset:192
	global_load_dwordx4 v[126:129], v[6:7], off offset:224
	v_mov_b32_e32 v131, s51
	v_lshlrev_b64 v[6:7], 9, v[130:131]
	v_lshlrev_b32_e32 v22, 2, v8
	v_lshl_add_u64 v[16:17], s[6:7], 0, v[6:7]
	v_bfe_u32 v23, v8, 2, 2
	v_and_b32_e32 v22, 12, v22
	v_lshlrev_b32_e32 v141, 8, v12
	v_lshlrev_b32_e32 v12, 3, v8
	v_or_b32_e32 v24, v22, v23
	v_lshrrev_b32_e32 v10, 3, v8
	s_waitcnt vmcnt(0)
	global_load_dwordx2 v[132:133], v[16:17], off
	v_mov_b32_e32 v16, 0x4000
	v_and_or_b32 v142, v12, 8, v16
	v_bitop3_b32 v12, v22, v9, v23 bitop3:0x36
	v_lshlrev_b32_e32 v143, 4, v12
	v_bitop3_b32 v12, v9, v24, 2 bitop3:0x36
	v_lshlrev_b32_e32 v144, 4, v12
	v_bitop3_b32 v12, v9, v24, 4 bitop3:0x36
	v_lshlrev_b32_e32 v145, 4, v12
	v_bitop3_b32 v12, v9, v24, 6 bitop3:0x36
	v_lshlrev_b32_e32 v146, 4, v12
	v_bitop3_b32 v12, v9, v24, 8 bitop3:0x36
	v_lshlrev_b32_e32 v147, 4, v12
	v_bitop3_b32 v12, v9, v24, 10 bitop3:0x36
	v_and_b32_e32 v11, 2, v10
	v_bfe_u32 v13, v8, 1, 1
	v_lshlrev_b32_e32 v148, 4, v12
	v_bitop3_b32 v12, v9, v24, 12 bitop3:0x36
	v_lshlrev_b32_e32 v140, 2, v9
	v_or_b32_e32 v10, v13, v11
	v_lshlrev_b32_e32 v149, 4, v12
	v_bitop3_b32 v12, v9, v24, 14 bitop3:0x36
	v_or_b32_e32 v14, v140, v23
	v_bitop3_b32 v15, v13, v9, v11 bitop3:0x36
	v_bitop3_b32 v13, v9, v10, 2 bitop3:0x36
	v_lshlrev_b32_e32 v150, 4, v12
	v_and_b32_e32 v12, 12, v8
	v_lshlrev_b32_e32 v151, 8, v14
	v_or_b32_e32 v14, v15, v12
	v_or_b32_e32 v12, v13, v12
	v_or_b32_e32 v11, 2, v9
	v_lshlrev_b32_e32 v154, 4, v12
	v_bitop3_b32 v12, v8, 4, 12 bitop3:0x6c
	s_mov_b64 s[0:1], 0x2d990000
	s_add_i32 s33, s33, 4
	v_bitop3_b32 v13, v10, v12, v9 bitop3:0xde
	v_bitop3_b32 v12, v11, v12, v10 bitop3:0xde
	v_lshl_add_u64 v[134:135], v[6:7], 0, s[0:1]
	s_lshl_b32 s0, s12, 8
	v_lshlrev_b32_e32 v178, 4, v12
	v_bitop3_b32 v12, v8, 8, 12 bitop3:0x6c
	v_bitop3_b32 v8, v8, 12, v8 bitop3:0xc
	s_add_u32 s0, s0, s13
	v_lshlrev_b32_e32 v177, 4, v13
	v_bitop3_b32 v13, v10, v12, v9 bitop3:0xde
	v_bitop3_b32 v9, v10, v8, v9 bitop3:0xde
	v_bitop3_b32 v8, v11, v8, v10 bitop3:0xde
	s_addc_u32 s1, 0, 0
	v_lshlrev_b32_e32 v182, 4, v8
	v_or_b32_e32 v8, 4, v0
	v_mov_b64_e32 v[6:7], s[0:1]
	v_lshlrev_b32_e32 v181, 4, v9
	v_mad_u64_u32 v[8:9], s[0:1], v8, s84, v[6:7]
	v_lshlrev_b32_e32 v152, 4, v14
	v_bitop3_b32 v12, v11, v12, v10 bitop3:0xde
	v_lshl_add_u64 v[136:137], v[8:9], 0, v[4:5]
	v_mad_u64_u32 v[4:5], s[0:1], v0, s84, v[6:7]
	v_mov_b32_e32 v14, v1
	v_mov_b32_e32 v15, v1
	s_waitcnt vmcnt(0)
	s_waitcnt vmcnt(0) lgkmcnt(0)
	s_barrier
; #define WAIT_TILE(all_) do { if (all_) asm volatile("s_waitcnt vmcnt(0) lgkmcnt(0)" ::: "memory"); \
;         else if constexpr (MODE == 0) asm volatile("s_waitcnt vmcnt(5) lgkmcnt(0)" ::: "memory"); else asm volatile("s_waitcnt vmcnt(4) lgkmcnt(0)" ::: "memory"); \
;         __builtin_amdgcn_s_barrier(); asm volatile("" ::: "memory"); } while (0)
; template <int MODE>
; __device__ __forceinline__ void attn_unit(LAS char* lds, const AttnPtrs& A, int b, int qb) {
;     ...
;     f32x16 o1[4];
; #pragma unroll
;     for (int c = 0; c < 4; ++c) o1[c] = f32x16{};
;     float m1 = -1e30f, l1 = 0.f;
;     unsigned long long mw_next = 0ull;
;     if constexpr (MODE == 1) { mw_next = A.MASK[qrow * 64]; asm volatile("" : "+v"(mw_next)); }
;     bf16x8 pk[4]; float a1 = 1.f;
;     ...
;     WAIT_TILE(true);
;     int st_cur = 0, st_nn = 2;
;     for (int t = 0; t < NT; ++t) {
	v_lshlrev_b32_e32 v179, 4, v13
	v_lshlrev_b32_e32 v180, 4, v12
	v_lshl_add_u64 v[138:139], v[4:5], 0, v[2:3]
	v_mov_b32_e32 v0, v1
	v_mov_b32_e32 v2, v1
	v_mov_b32_e32 v4, v1
	v_mov_b32_e32 v5, v1
	v_mov_b32_e32 v6, v1
	v_mov_b32_e32 v7, v1
	v_mov_b32_e32 v8, v1
	v_mov_b32_e32 v9, v1
	v_mov_b32_e32 v10, v1
	v_mov_b32_e32 v11, v1
	v_mov_b32_e32 v12, v1
	v_mov_b32_e32 v13, v1
	v_mov_b64_e32 v[64:65], v[14:15]
	v_mov_b64_e32 v[48:49], v[14:15]
	v_mov_b64_e32 v[32:33], v[14:15]
	v_mov_b64_e32 v[62:63], v[12:13]
	v_mov_b64_e32 v[60:61], v[10:11]
	v_mov_b64_e32 v[58:59], v[8:9]
	v_mov_b64_e32 v[56:57], v[6:7]
	v_mov_b64_e32 v[54:55], v[4:5]
	v_mov_b64_e32 v[52:53], v[2:3]
	v_mov_b64_e32 v[50:51], v[0:1]
	v_mov_b64_e32 v[46:47], v[12:13]
	v_mov_b64_e32 v[44:45], v[10:11]
	v_mov_b64_e32 v[42:43], v[8:9]
	v_mov_b64_e32 v[40:41], v[6:7]
	v_mov_b64_e32 v[38:39], v[4:5]
	v_mov_b64_e32 v[36:37], v[2:3]
	v_mov_b64_e32 v[34:35], v[0:1]
	v_mov_b64_e32 v[30:31], v[12:13]
	v_mov_b64_e32 v[28:29], v[10:11]
	v_mov_b64_e32 v[26:27], v[8:9]
	v_mov_b64_e32 v[24:25], v[6:7]
	v_mov_b64_e32 v[22:23], v[4:5]
	v_mov_b64_e32 v[20:21], v[2:3]
	v_mov_b64_e32 v[18:19], v[0:1]
	v_mov_b64_e32 v[16:17], v[14:15]
	s_mov_b32 s17, 0
	v_or_b32_e32 v153, 0x800, v151
	v_or_b32_e32 v155, 0x1000, v151
	v_or_b32_e32 v156, 0x1800, v151
	v_or_b32_e32 v157, 0x2000, v151
	v_or_b32_e32 v158, 0x2800, v151
	v_or_b32_e32 v159, 0x3000, v151
	v_or_b32_e32 v176, 0x3800, v151
	v_mov_b32_e32 v184, 0xf149f2ca
	v_mov_b32_e32 v253, s97
	v_mov_b32_e32 v252, 0
	v_mov_b64_e32 v[236:237], 0
	v_mov_b64_e32 v[238:239], 0
	v_mov_b64_e32 v[240:241], 0
	v_mov_b64_e32 v[242:243], 0
	v_mov_b64_e32 v[244:245], 0
	v_mov_b64_e32 v[246:247], 0
	v_mov_b64_e32 v[248:249], 0
	v_mov_b64_e32 v[250:251], 0
	v_mov_b32_e32 v183, 0
	v_mov_b64_e32 v[14:15], v[12:13]
	v_mov_b64_e32 v[12:13], v[10:11]
	v_mov_b64_e32 v[10:11], v[8:9]
	v_mov_b64_e32 v[8:9], v[6:7]
	v_mov_b64_e32 v[6:7], v[4:5]
	v_mov_b64_e32 v[4:5], v[2:3]
	v_mov_b64_e32 v[2:3], v[0:1]
	s_add_u32 s62, s2, s64
	s_addc_u32 s63, s3, s65
	s_add_u32 s66, s2, s30
	s_addc_u32 s67, s3, s31
	s_mov_b64 s[70:71], s[2:3]
	s_mov_b32 s50, 0
	s_cmp_le_i32 s50, s18
	s_cselect_b64 s[12:13], -1, 0
	s_cmp_gt_i32 s50, s18
	s_cbranch_scc1 .LBB0_1171
	s_branch .LBB0_1172

; template <int MODE>
; __device__ __forceinline__ void attn_unit(LAS char* lds, const AttnPtrs& A, int b, int qb) {
;     ...
;         if constexpr (MODE == 1) { if (t <= cw) {
;             const unsigned long long w = mw_next; mlo = (unsigned)w >> (4 * hi); mhi = (unsigned)(w >> 32) >> (4 * hi);
;             asm volatile("" : "+v"(mlo), "+v"(mhi));
;             if (t < cw) { const unsigned long long* mp_ = A.MASK + qrow * 64 + t + 1; asm volatile("global_load_dwordx2 %0, %1, off" : "+v"(mw_next) : "v"(mp_) : "memory"); } } }
;         const bool more2 = (t + 2 < NT);
;         if (more2) STAGE(t + 2, st_nn);
.LBB0_1172:
	v_lshrrev_b32_e32 v185, v140, v132
	v_lshrrev_b32_e32 v0, v140, v133
	s_cmp_ge_i32 s50, s18
	s_cbranch_scc1 .LBB0_1174
	global_load_dwordx2 v[132:133], v134, s[70:71] offset:8
.LBB0_1174:
	s_add_i32 s0, s50, 2
	s_cmp_ge_u32 s0, s33
	s_cselect_b64 s[0:1], -1, 0
	s_and_b64 vcc, exec, s[0:1]
	s_cbranch_vccnz .LBB0_1176
	s_mul_i32 s51, s16, 0xa000
	s_add_i32 s51, s19, s51
	s_mov_b32 m0, s51
	s_nop 0
	global_load_lds_dwordx4 v138, s[62:63]
	s_add_i32 m0, s51, 0x400
	s_nop 0
	global_load_lds_dwordx4 v136, s[62:63]
	s_add_i32 m0, s51, 0x4000
	s_nop 0
	global_load_lds_dwordx4 v138, s[66:67]
	s_add_i32 m0, s51, 0x4400
	s_nop 0
	global_load_lds_dwordx4 v136, s[66:67]

; __device__ __forceinline__ unsigned cvtpk(float lo, float hi) { unsigned r; asm("v_cvt_pk_bf16_f32 %0, %1, %2" : "=v"(r) : "v"(lo), "v"(hi)); return r; }
; __device__ __forceinline__ float sum_x32(float v) { const unsigned u = __float_as_uint(v); auto r = __builtin_amdgcn_permlane32_swap(u, u, false, false); return __uint_as_float(r[0]) + __uint_as_float(r[1]); }
; __device__ __forceinline__ float bf_lo(unsigned w) { return __uint_as_float(w << 16); }
; __device__ __forceinline__ float bf_hi(unsigned w) { return __uint_as_float(w & 0xffff0000u); }
; template <int MODE>
; __device__ __forceinline__ void attn_unit(LAS char* lds, const AttnPtrs& A, int b, int qb) {
;     ...
;         st_cur = (st_cur == 2) ? 0 : st_cur + 1; st_nn = (st_nn == 2) ? 0 : st_nn + 1;
;     }
;     ...
;     l1 = sum_x32(l1); const float i1 = 1.0f / l1;
;     ...
;     const bf16_t* grow = A.G + qrow * 2048; bf16_t* orow = A.Go + qrow * 2048;
; #pragma unroll
;     for (int c = 0; c < 4; ++c)
; #pragma unroll
;         for (int rr = 0; rr < 4; ++rr) {
;             const int dv = 32 * c + 8 * rr + 4 * hi;
;             const u32x2 g = *(const u32x2*)(grow + dv);
;             float v[4];
; #pragma unroll
;             for (int e = 0; e < 4; ++e) v[e] = o1[c][4 * rr + e];
;             if (MODE == 2) { const f32x4 sg = *(const f32x4*)(A.subg + dv);
; #pragma unroll
;                 for (int e = 0; e < 4; ++e) v[e] *= rstd * sg[e]; }
;             else {
; #pragma unroll
;                 for (int e = 0; e < 4; ++e) v[e] *= i1; }
;             u32x2 w; w.x = cvtpk(v[0] * bf_lo(g.x), v[1] * bf_hi(g.x)); w.y = cvtpk(v[2] * bf_lo(g.y), v[3] * bf_hi(g.y));
;             *(u32x2*)(orow + dv) = w;
.LBB0_1184:
	s_add_i32 s0, s17, 1
	s_cmp_lg_u32 s17, 2
	s_cselect_b32 s17, s0, 0
	s_add_i32 s0, s16, 1
	s_barrier
	s_cmp_lg_u32 s16, 2
	s_cselect_b32 s16, s0, 0
	s_add_i32 s50, s50, 1
	s_add_u32 s70, s70, 8
	s_addc_u32 s71, s71, 0
	s_add_u32 s62, s62, s60
	s_addc_u32 s63, s63, s61
	s_add_u32 s66, s66, s60
	s_addc_u32 s67, s67, s61
	s_cmp_lg_u32 s33, s50
	s_cbranch_scc1 .LBB0_1170
	v_mov_b32_e32 v0, v183
	s_nop 1
	v_permlane32_swap_b32_e32 v183, v0
	v_add_f32_e32 v0, v183, v0
	v_div_scale_f32 v66, s[12:13], v0, v0, 1.0
	v_rcp_f32_e32 v67, v66
	s_lshl_b32 s0, s15, 1
	s_add_u32 s0, s27, s0
	s_addc_u32 s1, s28, 0
	v_fma_f32 v68, -v66, v67, 1.0
	v_fmac_f32_e32 v67, v68, v67
	v_div_scale_f32 v68, vcc, 1.0, v0, 1.0
	v_mul_f32_e32 v69, v68, v67
	v_fma_f32 v70, -v66, v69, v68
	v_fmac_f32_e32 v69, v70, v67
	v_fma_f32 v66, -v66, v69, v68
	v_div_fmas_f32 v66, v66, v67, v69
	v_div_fixup_f32 v68, v66, v0, 1.0
	v_lshlrev_b64 v[66:67], 12, v[130:131]
	v_lshl_add_u64 v[66:67], s[0:1], 0, v[66:67]
	v_lshlrev_b32_e32 v0, 1, v140
	v_lshl_add_u64 v[66:67], v[66:67], 0, v[0:1]
	s_mov_b64 s[0:1], 0
	global_load_dwordx2 v[70:71], v[66:67], off
	global_load_dwordx2 v[72:73], v[66:67], off offset:16
	global_load_dwordx2 v[74:75], v[66:67], off offset:32
	global_load_dwordx2 v[76:77], v[66:67], off offset:48
	global_load_dwordx2 v[78:79], v[66:67], off offset:64
	global_load_dwordx2 v[80:81], v[66:67], off offset:80
	global_load_dwordx2 v[82:83], v[66:67], off offset:96
	global_load_dwordx2 v[84:85], v[66:67], off offset:112
	global_load_dwordx2 v[86:87], v[66:67], off offset:128
	global_load_dwordx2 v[88:89], v[66:67], off offset:144
	global_load_dwordx2 v[90:91], v[66:67], off offset:160
	global_load_dwordx2 v[92:93], v[66:67], off offset:176
	global_load_dwordx2 v[94:95], v[66:67], off offset:192
	global_load_dwordx2 v[96:97], v[66:67], off offset:208
	global_load_dwordx2 v[160:161], v[66:67], off offset:224
	global_load_dwordx2 v[162:163], v[66:67], off offset:240
	v_mul_f32_e32 v164, v50, v68
	v_mul_f32_e32 v165, v51, v68
	v_mul_f32_e32 v166, v52, v68
	v_mul_f32_e32 v167, v53, v68
	s_waitcnt vmcnt(15)
	v_lshlrev_b32_e32 v168, 16, v70
	v_and_b32_e32 v169, 0xffff0000, v70
	v_lshlrev_b32_e32 v170, 16, v71
	v_and_b32_e32 v171, 0xffff0000, v71
	v_mul_f32_e32 v164, v164, v168
	v_mul_f32_e32 v165, v165, v169
	v_mul_f32_e32 v166, v166, v170
	v_mul_f32_e32 v167, v167, v171
	v_cvt_pk_bf16_f32 v70, v164, v165
	v_cvt_pk_bf16_f32 v71, v166, v167
	global_store_dwordx2 v[66:67], v[70:71], off
	v_mul_f32_e32 v164, v54, v68
	v_mul_f32_e32 v165, v55, v68
	v_mul_f32_e32 v166, v56, v68
	v_mul_f32_e32 v167, v57, v68
	s_waitcnt vmcnt(15)
	v_lshlrev_b32_e32 v168, 16, v72
	v_and_b32_e32 v169, 0xffff0000, v72
	v_lshlrev_b32_e32 v170, 16, v73
	v_and_b32_e32 v171, 0xffff0000, v73
	v_mul_f32_e32 v164, v164, v168
	v_mul_f32_e32 v165, v165, v169
	v_mul_f32_e32 v166, v166, v170
	v_mul_f32_e32 v167, v167, v171
	v_cvt_pk_bf16_f32 v72, v164, v165
	v_cvt_pk_bf16_f32 v73, v166, v167
	global_store_dwordx2 v[66:67], v[72:73], off offset:16
	v_mul_f32_e32 v164, v58, v68
	v_mul_f32_e32 v165, v59, v68
	v_mul_f32_e32 v166, v60, v68
	v_mul_f32_e32 v167, v61, v68
	s_waitcnt vmcnt(15)
	v_lshlrev_b32_e32 v168, 16, v74
	v_and_b32_e32 v169, 0xffff0000, v74
	v_lshlrev_b32_e32 v170, 16, v75
	v_and_b32_e32 v171, 0xffff0000, v75
	v_mul_f32_e32 v164, v164, v168
	v_mul_f32_e32 v165, v165, v169
	v_mul_f32_e32 v166, v166, v170
	v_mul_f32_e32 v167, v167, v171
	v_cvt_pk_bf16_f32 v74, v164, v165
	v_cvt_pk_bf16_f32 v75, v166, v167
	global_store_dwordx2 v[66:67], v[74:75], off offset:32
	v_mul_f32_e32 v164, v62, v68
	v_mul_f32_e32 v165, v63, v68
	v_mul_f32_e32 v166, v64, v68
	v_mul_f32_e32 v167, v65, v68
	s_waitcnt vmcnt(15)
	v_lshlrev_b32_e32 v168, 16, v76
	v_and_b32_e32 v169, 0xffff0000, v76
	v_lshlrev_b32_e32 v170, 16, v77
	v_and_b32_e32 v171, 0xffff0000, v77
	v_mul_f32_e32 v164, v164, v168
	v_mul_f32_e32 v165, v165, v169
	v_mul_f32_e32 v166, v166, v170
	v_mul_f32_e32 v167, v167, v171
	v_cvt_pk_bf16_f32 v76, v164, v165
	v_cvt_pk_bf16_f32 v77, v166, v167
	global_store_dwordx2 v[66:67], v[76:77], off offset:48
	v_mul_f32_e32 v164, v34, v68
	v_mul_f32_e32 v165, v35, v68
	v_mul_f32_e32 v166, v36, v68
	v_mul_f32_e32 v167, v37, v68
	s_waitcnt vmcnt(15)
	v_lshlrev_b32_e32 v168, 16, v78
	v_and_b32_e32 v169, 0xffff0000, v78
	v_lshlrev_b32_e32 v170, 16, v79
	v_and_b32_e32 v171, 0xffff0000, v79
	v_mul_f32_e32 v164, v164, v168
	v_mul_f32_e32 v165, v165, v169
	v_mul_f32_e32 v166, v166, v170
	v_mul_f32_e32 v167, v167, v171
	v_cvt_pk_bf16_f32 v78, v164, v165
	v_cvt_pk_bf16_f32 v79, v166, v167
	global_store_dwordx2 v[66:67], v[78:79], off offset:64
	v_mul_f32_e32 v164, v38, v68
	v_mul_f32_e32 v165, v39, v68
	v_mul_f32_e32 v166, v40, v68
	v_mul_f32_e32 v167, v41, v68
	s_waitcnt vmcnt(15)
	v_lshlrev_b32_e32 v168, 16, v80
	v_and_b32_e32 v169, 0xffff0000, v80
	v_lshlrev_b32_e32 v170, 16, v81
	v_and_b32_e32 v171, 0xffff0000, v81
	v_mul_f32_e32 v164, v164, v168
	v_mul_f32_e32 v165, v165, v169
	v_mul_f32_e32 v166, v166, v170
	v_mul_f32_e32 v167, v167, v171
	v_cvt_pk_bf16_f32 v80, v164, v165
	v_cvt_pk_bf16_f32 v81, v166, v167
	global_store_dwordx2 v[66:67], v[80:81], off offset:80
	v_mul_f32_e32 v164, v42, v68
	v_mul_f32_e32 v165, v43, v68
	v_mul_f32_e32 v166, v44, v68
	v_mul_f32_e32 v167, v45, v68
	s_waitcnt vmcnt(15)
; __device__ __forceinline__ unsigned cvtpk(float lo, float hi) { unsigned r; asm("v_cvt_pk_bf16_f32 %0, %1, %2" : "=v"(r) : "v"(lo), "v"(hi)); return r; }
; __device__ __forceinline__ float bf_lo(unsigned w) { return __uint_as_float(w << 16); }
; __device__ __forceinline__ float bf_hi(unsigned w) { return __uint_as_float(w & 0xffff0000u); }
; template <int MODE>
; __device__ __forceinline__ void attn_unit(LAS char* lds, const AttnPtrs& A, int b, int qb) {
;     ...
;     const bf16_t* grow = A.G + qrow * 2048; bf16_t* orow = A.Go + qrow * 2048;
; #pragma unroll
;     for (int c = 0; c < 4; ++c)
; #pragma unroll
;         for (int rr = 0; rr < 4; ++rr) {
;             const int dv = 32 * c + 8 * rr + 4 * hi;
;             const u32x2 g = *(const u32x2*)(grow + dv);
;             float v[4];
; #pragma unroll
;             for (int e = 0; e < 4; ++e) v[e] = o1[c][4 * rr + e];
;             if (MODE == 2) { const f32x4 sg = *(const f32x4*)(A.subg + dv);
; #pragma unroll
;                 for (int e = 0; e < 4; ++e) v[e] *= rstd * sg[e]; }
;             else {
; #pragma unroll
;                 for (int e = 0; e < 4; ++e) v[e] *= i1; }
;             u32x2 w; w.x = cvtpk(v[0] * bf_lo(g.x), v[1] * bf_hi(g.x)); w.y = cvtpk(v[2] * bf_lo(g.y), v[3] * bf_hi(g.y));
;             *(u32x2*)(orow + dv) = w;
	v_lshlrev_b32_e32 v168, 16, v82
	v_and_b32_e32 v169, 0xffff0000, v82
	v_lshlrev_b32_e32 v170, 16, v83
	v_and_b32_e32 v171, 0xffff0000, v83
	v_mul_f32_e32 v164, v164, v168
	v_mul_f32_e32 v165, v165, v169
	v_mul_f32_e32 v166, v166, v170
	v_mul_f32_e32 v167, v167, v171
	v_cvt_pk_bf16_f32 v82, v164, v165
	v_cvt_pk_bf16_f32 v83, v166, v167
	global_store_dwordx2 v[66:67], v[82:83], off offset:96
	v_mul_f32_e32 v164, v46, v68
	v_mul_f32_e32 v165, v47, v68
	v_mul_f32_e32 v166, v48, v68
	v_mul_f32_e32 v167, v49, v68
	s_waitcnt vmcnt(15)
	v_lshlrev_b32_e32 v168, 16, v84
	v_and_b32_e32 v169, 0xffff0000, v84
	v_lshlrev_b32_e32 v170, 16, v85
	v_and_b32_e32 v171, 0xffff0000, v85
	v_mul_f32_e32 v164, v164, v168
	v_mul_f32_e32 v165, v165, v169
	v_mul_f32_e32 v166, v166, v170
	v_mul_f32_e32 v167, v167, v171
	v_cvt_pk_bf16_f32 v84, v164, v165
	v_cvt_pk_bf16_f32 v85, v166, v167
	global_store_dwordx2 v[66:67], v[84:85], off offset:112
	v_mul_f32_e32 v164, v18, v68
	v_mul_f32_e32 v165, v19, v68
	v_mul_f32_e32 v166, v20, v68
	v_mul_f32_e32 v167, v21, v68
	s_waitcnt vmcnt(15)
	v_lshlrev_b32_e32 v168, 16, v86
	v_and_b32_e32 v169, 0xffff0000, v86
	v_lshlrev_b32_e32 v170, 16, v87
	v_and_b32_e32 v171, 0xffff0000, v87
	v_mul_f32_e32 v164, v164, v168
	v_mul_f32_e32 v165, v165, v169
	v_mul_f32_e32 v166, v166, v170
	v_mul_f32_e32 v167, v167, v171
	v_cvt_pk_bf16_f32 v86, v164, v165
	v_cvt_pk_bf16_f32 v87, v166, v167
	global_store_dwordx2 v[66:67], v[86:87], off offset:128
	v_mul_f32_e32 v164, v22, v68
	v_mul_f32_e32 v165, v23, v68
	v_mul_f32_e32 v166, v24, v68
	v_mul_f32_e32 v167, v25, v68
	s_waitcnt vmcnt(15)
	v_lshlrev_b32_e32 v168, 16, v88
	v_and_b32_e32 v169, 0xffff0000, v88
	v_lshlrev_b32_e32 v170, 16, v89
	v_and_b32_e32 v171, 0xffff0000, v89
	v_mul_f32_e32 v164, v164, v168
	v_mul_f32_e32 v165, v165, v169
	v_mul_f32_e32 v166, v166, v170
	v_mul_f32_e32 v167, v167, v171
	v_cvt_pk_bf16_f32 v88, v164, v165
	v_cvt_pk_bf16_f32 v89, v166, v167
	global_store_dwordx2 v[66:67], v[88:89], off offset:144
	v_mul_f32_e32 v164, v26, v68
	v_mul_f32_e32 v165, v27, v68
	v_mul_f32_e32 v166, v28, v68
	v_mul_f32_e32 v167, v29, v68
	s_waitcnt vmcnt(15)
	v_lshlrev_b32_e32 v168, 16, v90
	v_and_b32_e32 v169, 0xffff0000, v90
	v_lshlrev_b32_e32 v170, 16, v91
	v_and_b32_e32 v171, 0xffff0000, v91
	v_mul_f32_e32 v164, v164, v168
	v_mul_f32_e32 v165, v165, v169
	v_mul_f32_e32 v166, v166, v170
	v_mul_f32_e32 v167, v167, v171
	v_cvt_pk_bf16_f32 v90, v164, v165
	v_cvt_pk_bf16_f32 v91, v166, v167
	global_store_dwordx2 v[66:67], v[90:91], off offset:160
	v_mul_f32_e32 v164, v30, v68
	v_mul_f32_e32 v165, v31, v68
	v_mul_f32_e32 v166, v32, v68
	v_mul_f32_e32 v167, v33, v68
	s_waitcnt vmcnt(15)
	v_lshlrev_b32_e32 v168, 16, v92
	v_and_b32_e32 v169, 0xffff0000, v92
	v_lshlrev_b32_e32 v170, 16, v93
	v_and_b32_e32 v171, 0xffff0000, v93
	v_mul_f32_e32 v164, v164, v168
	v_mul_f32_e32 v165, v165, v169
	v_mul_f32_e32 v166, v166, v170
	v_mul_f32_e32 v167, v167, v171
	v_cvt_pk_bf16_f32 v92, v164, v165
	v_cvt_pk_bf16_f32 v93, v166, v167
	global_store_dwordx2 v[66:67], v[92:93], off offset:176
	v_mul_f32_e32 v164, v2, v68
	v_mul_f32_e32 v165, v3, v68
	v_mul_f32_e32 v166, v4, v68
	v_mul_f32_e32 v167, v5, v68
	s_waitcnt vmcnt(15)
	v_lshlrev_b32_e32 v168, 16, v94
	v_and_b32_e32 v169, 0xffff0000, v94
	v_lshlrev_b32_e32 v170, 16, v95
	v_and_b32_e32 v171, 0xffff0000, v95
	v_mul_f32_e32 v164, v164, v168
	v_mul_f32_e32 v165, v165, v169
	v_mul_f32_e32 v166, v166, v170
	v_mul_f32_e32 v167, v167, v171
	v_cvt_pk_bf16_f32 v94, v164, v165
	v_cvt_pk_bf16_f32 v95, v166, v167
	global_store_dwordx2 v[66:67], v[94:95], off offset:192
	v_mul_f32_e32 v164, v6, v68
	v_mul_f32_e32 v165, v7, v68
	v_mul_f32_e32 v166, v8, v68
	v_mul_f32_e32 v167, v9, v68
	s_waitcnt vmcnt(15)
	v_lshlrev_b32_e32 v168, 16, v96
	v_and_b32_e32 v169, 0xffff0000, v96
	v_lshlrev_b32_e32 v170, 16, v97
	v_and_b32_e32 v171, 0xffff0000, v97
	v_mul_f32_e32 v164, v164, v168
	v_mul_f32_e32 v165, v165, v169
	v_mul_f32_e32 v166, v166, v170
	v_mul_f32_e32 v167, v167, v171
	v_cvt_pk_bf16_f32 v96, v164, v165
	v_cvt_pk_bf16_f32 v97, v166, v167
	global_store_dwordx2 v[66:67], v[96:97], off offset:208
	v_mul_f32_e32 v164, v10, v68
	v_mul_f32_e32 v165, v11, v68
	v_mul_f32_e32 v166, v12, v68
	v_mul_f32_e32 v167, v13, v68
	s_waitcnt vmcnt(15)
	v_lshlrev_b32_e32 v168, 16, v160
	v_and_b32_e32 v169, 0xffff0000, v160
	v_lshlrev_b32_e32 v170, 16, v161
	v_and_b32_e32 v171, 0xffff0000, v161
	v_mul_f32_e32 v164, v164, v168
	v_mul_f32_e32 v165, v165, v169
	v_mul_f32_e32 v166, v166, v170
	v_mul_f32_e32 v167, v167, v171
	v_cvt_pk_bf16_f32 v160, v164, v165
	v_cvt_pk_bf16_f32 v161, v166, v167
	global_store_dwordx2 v[66:67], v[160:161], off offset:224
	v_mul_f32_e32 v164, v14, v68
	v_mul_f32_e32 v165, v15, v68
	v_mul_f32_e32 v166, v16, v68
	v_mul_f32_e32 v167, v17, v68
	s_waitcnt vmcnt(15)
	v_lshlrev_b32_e32 v168, 16, v162
	v_and_b32_e32 v169, 0xffff0000, v162
	v_lshlrev_b32_e32 v170, 16, v163
	v_and_b32_e32 v171, 0xffff0000, v163
	v_mul_f32_e32 v164, v164, v168
	v_mul_f32_e32 v165, v165, v169
	v_mul_f32_e32 v166, v166, v170
	v_mul_f32_e32 v167, v167, v171
	v_cvt_pk_bf16_f32 v162, v164, v165
	v_cvt_pk_bf16_f32 v163, v166, v167
	global_store_dwordx2 v[66:67], v[162:163], off offset:240
